# GEMM phase prologues: K-tile-1 staging loads issued together with K-tile-0 (before the first prologue wait, counted vmcnt 8)
# baseline (speedup 1.0000x reference)
.LBB0_144:
	s_add_u32 s8, s4, 0x19000000
	s_addc_u32 s9, s5, 0
	s_lshl_b32 s4, s12, 5
	s_mov_b64 s[12:13], 0x80
	s_and_b32 s19, s4, 0x60
	s_add_i32 m0, s51, 0x18000
	v_lshl_add_u64 v[6:7], v[6:7], 0, s[12:13]
	s_lshl_b32 s18, s16, 13
	s_lshl_b32 s20, s19, 7
	global_load_lds_dwordx4 v[6:7], off
	v_lshl_add_u64 v[4:5], v[4:5], 0, s[12:13]
	s_add_i32 m0, s51, 0x1a000
	s_add_i32 s66, s51, 0x8000
	s_add_i32 s67, s51, 0xa000
	global_load_lds_dwordx4 v[4:5], off
	v_lshl_add_u64 v[0:1], v[0:1], 0, s[12:13]
	s_mov_b32 m0, s66
	s_add_u32 s4, s54, 0x10080
	global_load_lds_dwordx4 v[0:1], off
	v_lshl_add_u64 v[0:1], v[2:3], 0, s[12:13]
	s_mov_b32 m0, s67
	s_addc_u32 s5, s55, 0
	global_load_lds_dwordx4 v[0:1], off
	s_add_i32 m0, s51, 0x1c000
	v_lshl_add_u64 v[0:1], s[4:5], 0, v[130:131]
	global_load_lds_dwordx4 v[0:1], off
	v_lshl_add_u64 v[0:1], s[4:5], 0, v[134:135]
	s_add_i32 m0, s51, 0x1e000
	s_nop 0
	global_load_lds_dwordx4 v[0:1], off
	s_waitcnt vmcnt(8)
	s_barrier
	s_cmpk_lt_u32 s15, 0x100
	v_lshrrev_b32_e32 v1, 1, v8
	v_and_b32_e32 v1, 24, v1
	v_and_b32_e32 v0, 15, v8
	v_lshlrev_b32_e32 v2, 1, v1
	s_sext_i32_i8 s78, s14
	v_lshl_or_b32 v142, s16, 6, v0
	v_lshl_or_b32 v0, v0, 6, v2
	v_lshlrev_b32_e32 v2, 2, v8
	s_cselect_b64 s[14:15], -1, 0
	s_ashr_i32 s70, s42, 31
	v_and_b32_e32 v2, 32, v2
	s_waitcnt vmcnt(6)
	s_add_u32 s16, s2, s42
	v_bitop3_b32 v3, v0, s18, v2 bitop3:0xde
	v_bitop3_b32 v143, v0, s20, v2 bitop3:0xde
	s_addc_u32 s17, s17, s70
	s_add_i32 s72, 0, 0x10000
	s_add_i32 s73, 0, 0x14000
	s_mov_b32 s71, s42
	v_or_b32_e32 v144, s19, v1
	s_mov_b64 s[18:19], 0x100
	v_add_u32_e32 v145, s72, v143
	v_add_u32_e32 v146, s73, v143
	v_add_u32_e32 v147, 0, v3
	s_mov_b64 s[20:21], 0x180
	s_mov_b64 s[22:23], 0x80000
	s_mov_b32 s74, 0x80000
	s_mov_b64 s[24:25], 0x90000
	s_mov_b32 s75, 0x90000
	s_mov_b64 s[26:27], 0xa0000
	s_mov_b32 s76, 0xa0000
	s_mov_b64 s[30:31], 0xb0000
	s_mov_b32 s77, 0xb0000
	s_barrier
	s_branch .LBB0_147

.LBB0_168:
	s_add_u32 s18, s8, 0x11800000
	s_addc_u32 s19, s9, 0
	s_add_u32 s20, s8, 0x400000
	s_mov_b64 s[22:23], 0x80
	s_addc_u32 s21, s9, 0
	s_and_b32 s56, s4, 3
	s_add_i32 m0, s13, 0x18000
	v_lshl_add_u64 v[6:7], v[6:7], 0, s[22:23]
	s_lshl_b32 s4, s5, 13
	s_lshl_b32 s25, s56, 12
	global_load_lds_dwordx4 v[6:7], off
	v_lshl_add_u64 v[4:5], v[4:5], 0, s[22:23]
	s_add_i32 m0, s13, 0x1a000
	s_add_i32 s57, s13, 0x8000
	s_add_i32 s58, s13, 0xa000
	global_load_lds_dwordx4 v[4:5], off
	v_lshl_add_u64 v[0:1], v[0:1], 0, s[22:23]
	s_mov_b32 m0, s57
	s_add_u32 s26, s46, 0x80080
	global_load_lds_dwordx4 v[0:1], off
	v_lshl_add_u64 v[0:1], v[2:3], 0, s[22:23]
	s_mov_b32 m0, s58
	s_addc_u32 s27, s47, 0
	global_load_lds_dwordx4 v[0:1], off
	s_add_i32 m0, s13, 0x1c000
	v_lshl_add_u64 v[0:1], s[26:27], 0, v[130:131]
	global_load_lds_dwordx4 v[0:1], off
	v_lshl_add_u64 v[0:1], s[26:27], 0, v[134:135]
	s_add_i32 m0, s13, 0x1e000
	s_nop 0
	global_load_lds_dwordx4 v[0:1], off
	s_waitcnt vmcnt(8)
	s_barrier
	s_cmpk_lt_u32 s24, 0x100
	v_bfe_u32 v1, v8, 4, 2
	v_and_b32_e32 v0, 15, v8
	v_lshlrev_b32_e32 v3, 4, v1
	v_lshl_or_b32 v154, s5, 6, v0
	v_lshl_or_b32 v0, v0, 6, v3
	v_lshlrev_b32_e32 v3, 2, v8
	v_and_b32_e32 v3, 32, v3
	v_lshlrev_b32_e32 v2, 3, v1
	v_bitop3_b32 v4, v0, s4, v3 bitop3:0xde
	v_bitop3_b32 v155, v0, s25, v3 bitop3:0xde
	v_cmp_eq_u32_e64 s[4:5], 0, v1
	v_lshlrev_b32_e32 v0, 5, v1
	v_mov_b32_e32 v1, v136
	v_lshl_add_u64 v[138:139], s[8:9], 0, v[0:1]
	v_lshlrev_b32_e32 v0, 15, v12
	v_and_b32_e32 v0, 0xffff0000, v0
	v_lshl_add_u32 v0, v13, 12, v0
	v_and_b32_e32 v1, 1, v12
	v_lshl_or_b32 v0, v1, 6, v0
	v_lshl_add_u32 v140, v14, 1, v0
	v_lshlrev_b32_e32 v0, 15, v9
	v_and_b32_e32 v0, 0xffff0000, v0
	s_waitcnt vmcnt(6)
	v_lshl_add_u32 v0, v10, 12, v0
	v_and_b32_e32 v1, 1, v9
	s_cselect_b64 s[24:25], -1, 0
	v_lshl_or_b32 v0, v1, 6, v0
	s_add_i32 s62, 0, 0x10000
	s_add_i32 s63, 0, 0x14000
	v_lshl_or_b32 v156, s56, 5, v2
	s_ashr_i32 s59, s42, 31
	s_mov_b32 s60, s42
	s_ashr_i32 s61, s2, 31
	v_mov_b32_e32 v141, v136
	v_lshl_add_u32 v142, v11, 1, v0
	v_mov_b32_e32 v143, v136
	v_mov_b64_e32 v[144:145], 0x200
	v_mov_b64_e32 v[146:147], 0x1ff
	v_add_u32_e32 v157, s62, v155
	v_add_u32_e32 v158, s63, v155
	v_add_u32_e32 v159, 0, v4
	v_mbcnt_hi_u32_b32 v160, -1, v254
	v_mov_b32_e32 v161, 0x358637bd
	s_mov_b32 s64, 0x800000
	s_mov_b32 s65, 0
	s_barrier
	s_branch .LBB0_171

.LBB0_327:
	s_add_u32 s16, s8, 0xd800000
	s_addc_u32 s17, s9, 0
	s_add_u32 s18, s8, 0xf800000
	s_addc_u32 s19, s9, 0
	s_add_u32 s20, s8, 0x200000
	s_mov_b64 s[22:23], 0x80
	s_addc_u32 s21, s9, 0
	s_and_b32 s61, s10, 3
	s_add_i32 m0, s57, 0x18000
	v_lshl_add_u64 v[6:7], v[6:7], 0, s[22:23]
	s_lshl_b32 s10, s11, 13
	s_lshl_b32 s25, s61, 12
	global_load_lds_dwordx4 v[6:7], off
	v_lshl_add_u64 v[4:5], v[4:5], 0, s[22:23]
	s_add_i32 m0, s57, 0x1a000
	s_add_i32 s62, s57, 0x8000
	s_add_i32 s63, s57, 0xa000
	global_load_lds_dwordx4 v[4:5], off
	v_lshl_add_u64 v[0:1], v[0:1], 0, s[22:23]
	s_mov_b32 m0, s62
	s_add_u32 s8, s48, 0x80080
	global_load_lds_dwordx4 v[0:1], off
	v_lshl_add_u64 v[0:1], v[2:3], 0, s[22:23]
	s_mov_b32 m0, s63
	s_addc_u32 s9, s49, 0
	global_load_lds_dwordx4 v[0:1], off
	s_add_i32 m0, s57, 0x1c000
	v_lshl_add_u64 v[0:1], s[8:9], 0, v[130:131]
	global_load_lds_dwordx4 v[0:1], off
	v_lshl_add_u64 v[0:1], s[8:9], 0, v[134:135]
	s_add_i32 m0, s57, 0x1e000
	s_nop 0
	global_load_lds_dwordx4 v[0:1], off
	s_waitcnt vmcnt(8)
	s_barrier
	s_cmpk_lt_u32 s24, 0x100
	v_bfe_u32 v0, v8, 4, 2
	v_and_b32_e32 v1, 15, v8
	v_lshlrev_b32_e32 v3, 4, v0
	v_lshl_or_b32 v148, s11, 6, v1
	v_lshlrev_b32_e32 v2, 3, v0
	v_lshl_or_b32 v1, v1, 6, v3
	v_lshlrev_b32_e32 v3, 2, v8
	v_cmp_eq_u32_e64 s[8:9], 0, v0
	v_lshlrev_b32_e32 v0, 15, v12
	v_and_b32_e32 v3, 32, v3
	v_and_b32_e32 v0, 0xffff0000, v0
	v_bitop3_b32 v4, v1, s10, v3 bitop3:0xde
	v_bitop3_b32 v149, v1, s25, v3 bitop3:0xde
	v_lshl_add_u32 v0, v13, 12, v0
	v_and_b32_e32 v1, 1, v12
	v_lshl_or_b32 v0, v1, 6, v0
	v_lshl_add_u32 v136, v14, 1, v0
	v_lshlrev_b32_e32 v0, 15, v9
	v_and_b32_e32 v0, 0xffff0000, v0
	s_waitcnt vmcnt(6)
	v_lshl_add_u32 v0, v10, 12, v0
	v_and_b32_e32 v1, 1, v9
	s_cselect_b64 s[24:25], -1, 0
	v_lshl_or_b32 v0, v1, 6, v0
	s_add_i32 s66, 0, 0x10000
	s_add_i32 s67, 0, 0x14000
	v_lshl_or_b32 v150, s61, 5, v2
	s_mov_b32 s64, s42
	s_ashr_i32 s65, s2, 31
	v_mov_b32_e32 v137, v131
	v_lshl_add_u32 v138, v11, 1, v0
	v_mov_b32_e32 v139, v131
	v_mov_b64_e32 v[140:141], 0x100
	v_mov_b64_e32 v[142:143], 0xff
	v_add_u32_e32 v151, s66, v149
	v_add_u32_e32 v152, s67, v149
	v_add_u32_e32 v153, 0, v4
	v_mbcnt_hi_u32_b32 v154, -1, v254
	s_mov_b32 s70, 0
	s_barrier
	s_branch .LBB0_330

.LBB0_420:
	v_bfe_u32 v17, v12, 4, 2
	s_sext_i32_i16 s51, s14
	s_add_u32 s14, s8, 0x11800000
	v_and_b32_e32 v16, 15, v12
	v_lshlrev_b32_e32 v18, 4, v17
	v_lshlrev_b32_e32 v12, 2, v12
	s_addc_u32 s15, s9, 0
	v_lshl_or_b32 v219, s16, 6, v16
	v_lshl_or_b32 v16, v16, 6, v18
	s_lshl_b32 s16, s16, 13
	v_and_b32_e32 v12, 32, v12
	v_bitop3_b32 v18, v16, s16, v12 bitop3:0xde
	s_lshl_b32 s16, s20, 5
	s_and_b32 s22, s16, 0x60
	s_lshl_b32 s16, s22, 7
	v_bitop3_b32 v220, v16, s16, v12 bitop3:0xde
	s_mov_b64 s[16:17], 0x80
	s_add_i32 m0, s37, 0x18000
	v_lshl_add_u64 v[8:9], v[8:9], 0, s[16:17]
	global_load_lds_dwordx4 v[8:9], off
	v_lshl_add_u64 v[6:7], v[6:7], 0, s[16:17]
	s_add_i32 m0, s37, 0x1a000
	s_add_i32 s63, s37, 0x8000
	s_add_i32 s64, s37, 0xa000
	global_load_lds_dwordx4 v[6:7], off
	v_lshl_add_u64 v[2:3], v[2:3], 0, s[16:17]
	s_mov_b32 m0, s63
	s_add_u32 s20, s10, 0x80080
	global_load_lds_dwordx4 v[2:3], off
	v_lshl_add_u64 v[2:3], v[4:5], 0, s[16:17]
	s_mov_b32 m0, s64
	s_addc_u32 s21, s11, 0
	global_load_lds_dwordx4 v[2:3], off
	s_add_i32 m0, s37, 0x1c000
	v_lshl_add_u64 v[2:3], s[20:21], 0, v[198:199]
	global_load_lds_dwordx4 v[2:3], off
	v_lshl_add_u64 v[2:3], s[20:21], 0, v[202:203]
	s_add_i32 m0, s37, 0x1e000
	s_nop 0
	global_load_lds_dwordx4 v[2:3], off
	s_waitcnt vmcnt(8)
	s_barrier
	s_cmpk_lt_u32 s18, 0x100
	s_mul_i32 s20, s77, s73
	s_mul_hi_u32 s21, s77, s42
	s_cselect_b64 s[18:19], -1, 0
	s_add_i32 s20, s21, s20
	v_readlane_b32 s21, v255, 10
	s_mul_i32 s24, s77, s42
	s_add_u32 s24, s24, s21
	v_readlane_b32 s21, v255, 11
	s_addc_u32 s25, s20, s21
	s_cmpk_lt_i32 s24, 0x580
	s_cselect_b64 s[20:21], -1, 0
	s_ashr_i32 s26, s24, 31
	s_lshr_b32 s26, s26, 29
	s_add_i32 s26, s24, s26
	s_ashr_i32 s27, s26, 3
	s_and_b32 s26, s26, -8
	s_sub_i32 s26, s24, s26
	s_cmp_lt_i32 s26, 0
	s_cselect_b32 s30, s49, 0xb0
	s_mul_i32 s26, s30, s26
	s_add_i32 s26, s26, s27
	s_mul_hi_i32 s27, s26, 0x2e8ba2e9
	s_lshr_b32 s30, s27, 31
	s_ashr_i32 s27, s27, 6
	s_add_i32 s27, s27, s30
	s_lshl_b32 s30, s27, 3
	s_sub_i32 s31, 32, s30
	s_min_i32 s31, s31, 8
	s_abs_i32 s34, s31
	v_cvt_f32_u32_e32 v4, s34
	v_lshlrev_b32_e32 v2, 5, v17
	v_mov_b32_e32 v3, v0
	v_lshl_add_u64 v[2:3], s[8:9], 0, v[2:3]
	v_rcp_iflag_f32_e32 v4, v4
	s_mov_b64 s[8:9], 0x200000
	s_mulk_i32 s27, 0x160
	v_lshl_add_u64 v[204:205], v[2:3], 0, s[8:9]
	v_mul_f32_e32 v4, 0x4f7ffffe, v4
	v_cvt_u32_f32_e32 v4, v4
	s_sub_i32 s8, s26, s27
	s_sub_i32 s26, 0, s34
	v_lshl_or_b32 v221, v17, 3, s22
	v_readfirstlane_b32 s27, v4
	s_mul_i32 s26, s26, s27
	s_mul_hi_u32 s26, s27, s26
	s_abs_i32 s22, s8
	s_add_i32 s27, s27, s26
	s_mul_hi_u32 s26, s22, s27
	s_mul_i32 s27, s26, s34
	s_xor_b32 s9, s8, s31
	s_sub_i32 s22, s22, s27
	s_ashr_i32 s9, s9, 31
	s_add_i32 s27, s26, 1
	s_sub_i32 s35, s22, s34
	s_cmp_ge_u32 s22, s34
	s_cselect_b32 s26, s27, s26
	v_lshlrev_b32_e32 v4, 15, v13
	s_cselect_b32 s22, s35, s22
	s_add_i32 s27, s26, 1
	v_and_b32_e32 v4, 0xffff0000, v4
	s_cmp_ge_u32 s22, s34
	v_lshl_add_u32 v4, v14, 12, v4
	v_and_b32_e32 v5, 1, v13
	s_cselect_b32 s22, s27, s26
	v_lshl_or_b32 v4, v5, 6, v4
	s_xor_b32 s22, s22, s9
	v_lshl_add_u32 v206, v15, 1, v4
	v_lshlrev_b32_e32 v4, 15, v1
	s_sub_i32 s65, s22, s9
	v_and_b32_e32 v4, 0xffff0000, v4
	s_waitcnt vmcnt(6)
	s_mul_i32 s9, s65, s31
	v_lshl_add_u32 v4, v10, 12, v4
	v_and_b32_e32 v1, 1, v1
	v_mov_b64_e32 v[2:3], 0x580
	s_sub_i32 s66, s8, s9
	v_lshl_or_b32 v1, v1, 6, v4
	s_add_i32 s67, 0, 0x10000
	s_add_i32 s70, 0, 0x14000
	s_add_i32 s66, s66, s30
	v_mov_b32_e32 v207, v0
	v_lshl_add_u32 v208, v11, 1, v1
	v_mov_b32_e32 v209, v0
	v_cmp_lt_i64_e64 s[8:9], s[24:25], v[2:3]
	v_add_u32_e32 v222, s67, v220
	v_add_u32_e32 v223, s70, v220
	v_add_u32_e32 v224, 0, v18
	v_mbcnt_hi_u32_b32 v225, -1, v254
	v_mov_b32_e32 v226, 0x358637bd
	s_mov_b32 s71, 0x800000
	s_movk_i32 s72, 0x2c00
	v_mov_b64_e32 v[210:211], 0x57f
	s_barrier
	s_branch .LBB0_423

.LBB0_509:
	s_add_u32 s20, s14, 0xd800000
	s_addc_u32 s21, s15, 0
	s_add_u32 s22, s14, 0xf800000
	s_mov_b64 s[24:25], 0x80
	s_addc_u32 s23, s15, 0
	s_and_b32 s59, s8, 3
	s_add_i32 m0, s49, 0x18000
	v_lshl_add_u64 v[6:7], v[6:7], 0, s[24:25]
	s_lshl_b32 s8, s9, 13
	s_lshl_b32 s13, s59, 12
	global_load_lds_dwordx4 v[6:7], off
	v_lshl_add_u64 v[2:3], v[2:3], 0, s[24:25]
	s_add_i32 m0, s49, 0x1a000
	s_add_i32 s60, s49, 0x8000
	s_add_i32 s61, s49, 0xa000
	global_load_lds_dwordx4 v[2:3], off
	v_lshl_add_u64 v[0:1], v[0:1], 0, s[24:25]
	s_mov_b32 m0, s60
	s_add_u32 s26, s36, 0x160080
	global_load_lds_dwordx4 v[0:1], off
	v_lshl_add_u64 v[0:1], v[4:5], 0, s[24:25]
	s_mov_b32 m0, s61
	s_addc_u32 s27, s37, 0
	global_load_lds_dwordx4 v[0:1], off
	s_add_i32 m0, s49, 0x1c000
	v_lshl_add_u64 v[0:1], s[26:27], 0, v[130:131]
	global_load_lds_dwordx4 v[0:1], off
	v_lshl_add_u64 v[0:1], s[26:27], 0, v[134:135]
	s_add_i32 m0, s49, 0x1e000
	s_mov_b64 s[30:31], 0x160080
	global_load_lds_dwordx4 v[0:1], off
	s_waitcnt vmcnt(8)
	s_barrier
	v_bfe_u32 v0, v8, 4, 2
	v_and_b32_e32 v1, 15, v8
	v_lshlrev_b32_e32 v3, 4, v0
	v_lshl_or_b32 v148, s9, 6, v1
	v_lshl_or_b32 v1, v1, 6, v3
	v_lshlrev_b32_e32 v3, 2, v8
	v_and_b32_e32 v3, 32, v3
	v_lshlrev_b32_e32 v2, 3, v0
	v_bitop3_b32 v4, v1, s8, v3 bitop3:0xde
	v_bitop3_b32 v149, v1, s13, v3 bitop3:0xde
	v_cmp_eq_u32_e64 s[8:9], 0, v0
	v_lshrrev_b32_e32 v1, 1, v13
	v_mul_lo_u32 v0, v14, s11
	v_mad_u64_u32 v[0:1], s[46:47], v1, s12, v[0:1]
	v_or_b32_e32 v0, v0, v15
	v_add_lshl_u32 v0, v0, v16, 1
	v_mov_b32_e32 v1, v131
	v_lshl_add_u64 v[136:137], v[0:1], 0, s[30:31]
	v_lshrrev_b32_e32 v1, 1, v9
	v_mul_lo_u32 v0, v10, s11
	s_cmpk_lt_u32 s10, 0x100
	v_mad_u64_u32 v[0:1], s[10:11], v1, s12, v[0:1]
	s_waitcnt vmcnt(6)
	v_or_b32_e32 v0, v0, v11
	s_cselect_b64 s[26:27], -1, 0
	v_add_lshl_u32 v0, v0, v12, 1
	v_mov_b32_e32 v1, v131
	s_add_i32 s62, 0, 0x10000
	s_add_i32 s63, 0, 0x14000
	v_lshl_or_b32 v150, s59, 5, v2
	v_lshl_add_u64 v[138:139], v[0:1], 0, s[30:31]
	v_mov_b64_e32 v[140:141], 0x100
	v_mov_b64_e32 v[142:143], 0xff
	v_add_u32_e32 v151, s62, v149
	v_add_u32_e32 v152, s63, v149
	v_add_u32_e32 v153, 0, v4
	v_mbcnt_hi_u32_b32 v154, -1, v254
	s_mov_b32 s64, 0
	s_barrier
	s_branch .LBB0_512

.LBB0_607:
	s_add_u32 s18, s10, 0xf800000
	s_addc_u32 s19, s11, 0
	s_add_u32 s20, s10, 0x200000
	s_addc_u32 s21, s11, 0
	s_add_u32 s22, s10, 0x19000000
	s_mov_b64 s[24:25], 0x80
	s_addc_u32 s23, s11, 0
	s_and_b32 s63, s8, 3
	s_add_i32 m0, s45, 0x18000
	v_lshl_add_u64 v[6:7], v[6:7], 0, s[24:25]
	s_lshl_b32 s8, s9, 13
	s_lshl_b32 s27, s63, 12
	global_load_lds_dwordx4 v[6:7], off
	v_lshl_add_u64 v[4:5], v[4:5], 0, s[24:25]
	s_add_i32 m0, s45, 0x1a000
	s_add_i32 s64, s45, 0x8000
	s_add_i32 s65, s45, 0xa000
	global_load_lds_dwordx4 v[4:5], off
	v_lshl_add_u64 v[0:1], v[0:1], 0, s[24:25]
	s_mov_b32 m0, s64
	s_add_u32 s30, s56, 0x80080
	global_load_lds_dwordx4 v[0:1], off
	v_lshl_add_u64 v[0:1], v[2:3], 0, s[24:25]
	s_mov_b32 m0, s65
	s_addc_u32 s31, s57, 0
	global_load_lds_dwordx4 v[0:1], off
	s_add_i32 m0, s45, 0x1c000
	v_lshl_add_u64 v[0:1], s[30:31], 0, v[130:131]
	global_load_lds_dwordx4 v[0:1], off
	v_lshl_add_u64 v[0:1], s[30:31], 0, v[134:135]
	s_add_i32 m0, s45, 0x1e000
	s_nop 0
	global_load_lds_dwordx4 v[0:1], off
	s_waitcnt vmcnt(8)
	s_barrier
	s_cmpk_lt_u32 s26, 0x100
	v_bfe_u32 v1, v8, 4, 2
	v_and_b32_e32 v0, 15, v8
	v_lshlrev_b32_e32 v3, 4, v1
	v_lshl_or_b32 v156, s9, 6, v0
	v_lshl_or_b32 v0, v0, 6, v3
	v_lshlrev_b32_e32 v3, 2, v8
	v_and_b32_e32 v3, 32, v3
	v_lshlrev_b32_e32 v2, 3, v1
	v_bitop3_b32 v4, v0, s8, v3 bitop3:0xde
	v_bitop3_b32 v157, v0, s27, v3 bitop3:0xde
	v_cmp_eq_u32_e64 s[8:9], 0, v1
	v_lshlrev_b32_e32 v0, 5, v1
	v_mov_b32_e32 v1, v131
	v_lshl_add_u64 v[136:137], s[10:11], 0, v[0:1]
	v_lshlrev_b32_e32 v0, 15, v12
	v_and_b32_e32 v0, 0xffff0000, v0
	v_lshl_add_u32 v0, v13, 12, v0
	v_and_b32_e32 v1, 1, v12
	v_lshl_or_b32 v0, v1, 6, v0
	v_lshl_add_u32 v138, v14, 1, v0
	v_lshlrev_b32_e32 v0, 15, v9
	v_and_b32_e32 v0, 0xffff0000, v0
	s_waitcnt vmcnt(6)
	v_lshl_add_u32 v0, v10, 12, v0
	v_and_b32_e32 v1, 1, v9
	s_cselect_b64 s[26:27], -1, 0
	v_lshl_or_b32 v0, v1, 6, v0
	s_add_i32 s66, 0, 0x10000
	s_add_i32 s67, 0, 0x14000
	v_lshl_or_b32 v158, s63, 5, v2
	v_mov_b32_e32 v139, v131
	v_lshl_add_u32 v140, v11, 1, v0
	v_mov_b32_e32 v141, v131
	v_mov_b64_e32 v[142:143], 0x100
	v_mov_b64_e32 v[144:145], 0xff
	v_add_u32_e32 v159, s66, v157
	v_add_u32_e32 v160, s67, v157
	v_add_u32_e32 v161, 0, v4
	v_mbcnt_hi_u32_b32 v162, -1, v254
	v_mov_b32_e32 v163, 0x358637bd
	s_mov_b32 s70, 0x800000
	s_mov_b32 s71, 0
	s_barrier
	s_branch .LBB0_610

.LBB0_699:
	s_add_u32 s12, s8, 0x19000000
	s_addc_u32 s13, s9, 0
	s_lshl_b32 s8, s14, 5
	s_mov_b64 s[14:15], 0x80
	s_and_b32 s20, s8, 0x60
	s_add_i32 m0, s49, 0x18000
	v_lshl_add_u64 v[6:7], v[6:7], 0, s[14:15]
	s_lshl_b32 s19, s18, 13
	s_lshl_b32 s21, s20, 7
	global_load_lds_dwordx4 v[6:7], off
	v_lshl_add_u64 v[4:5], v[4:5], 0, s[14:15]
	s_add_i32 m0, s49, 0x1a000
	s_add_i32 s66, s49, 0x8000
	s_add_i32 s67, s49, 0xa000
	global_load_lds_dwordx4 v[4:5], off
	v_lshl_add_u64 v[0:1], v[0:1], 0, s[14:15]
	s_mov_b32 m0, s66
	s_add_u32 s8, s60, 0x10080
	global_load_lds_dwordx4 v[0:1], off
	v_lshl_add_u64 v[0:1], v[2:3], 0, s[14:15]
	s_mov_b32 m0, s67
	s_addc_u32 s9, s61, 0
	global_load_lds_dwordx4 v[0:1], off
	s_add_i32 m0, s49, 0x1c000
	v_lshl_add_u64 v[0:1], s[8:9], 0, v[130:131]
	global_load_lds_dwordx4 v[0:1], off
	v_lshl_add_u64 v[0:1], s[8:9], 0, v[134:135]
	s_add_i32 m0, s49, 0x1e000
	s_nop 0
	global_load_lds_dwordx4 v[0:1], off
	s_waitcnt vmcnt(8)
	s_barrier
	s_cmpk_lt_u32 s17, 0x100
	v_lshrrev_b32_e32 v1, 1, v8
	v_and_b32_e32 v1, 24, v1
	v_and_b32_e32 v0, 15, v8
	v_lshlrev_b32_e32 v2, 1, v1
	v_lshl_or_b32 v142, s18, 6, v0
	v_lshl_or_b32 v0, v0, 6, v2
	v_lshlrev_b32_e32 v2, 2, v8
	s_sext_i32_i8 s46, s16
	v_and_b32_e32 v2, 32, v2
	s_waitcnt vmcnt(6)
	s_cselect_b64 s[16:17], -1, 0
	s_add_u32 s18, s2, s42
	v_bitop3_b32 v3, v0, s19, v2 bitop3:0xde
	v_bitop3_b32 v143, v0, s21, v2 bitop3:0xde
	s_addc_u32 s19, s74, s73
	s_add_i32 s70, 0, 0x10000
	s_add_i32 s71, 0, 0x14000
	v_or_b32_e32 v144, s20, v1
	s_mov_b64 s[20:21], 0x100
	v_add_u32_e32 v145, s70, v143
	v_add_u32_e32 v146, s71, v143
	v_add_u32_e32 v147, 0, v3
	s_add_i32 s72, s49, 0xc000
	s_add_i32 s80, s49, 0xe000
	s_mov_b64 s[22:23], 0x180
	s_mov_b32 s81, 0x80000
	s_mov_b64 s[24:25], 0x90000
	s_mov_b32 s82, 0x90000
	s_mov_b64 s[26:27], 0xa0000
	s_mov_b32 s83, 0xa0000
	s_mov_b64 s[30:31], 0xb0000
	s_mov_b32 s84, 0xb0000
	s_barrier
	s_branch .LBB0_702

.LBB0_721:
	s_add_u32 s12, s8, 0x11800000
	s_addc_u32 s13, s9, 0
	s_lshl_b32 s14, s14, 5
	s_and_b32 s22, s14, 0x60
	s_mov_b64 s[14:15], 0x80
	s_add_i32 m0, s27, 0x18000
	v_lshl_add_u64 v[6:7], v[6:7], 0, s[14:15]
	s_lshl_b32 s19, s18, 13
	s_lshl_b32 s23, s22, 7
	global_load_lds_dwordx4 v[6:7], off
	v_lshl_add_u64 v[4:5], v[4:5], 0, s[14:15]
	s_add_i32 m0, s27, 0x1a000
	s_add_i32 s53, s27, 0x8000
	s_add_i32 s54, s27, 0xa000
	global_load_lds_dwordx4 v[4:5], off
	v_lshl_add_u64 v[0:1], v[0:1], 0, s[14:15]
	s_mov_b32 m0, s53
	s_add_u32 s20, s30, 0x80080
	global_load_lds_dwordx4 v[0:1], off
	v_lshl_add_u64 v[0:1], v[2:3], 0, s[14:15]
	s_mov_b32 m0, s54
	s_addc_u32 s21, s31, 0
	global_load_lds_dwordx4 v[0:1], off
	s_add_i32 m0, s27, 0x1c000
	v_lshl_add_u64 v[0:1], s[20:21], 0, v[130:131]
	global_load_lds_dwordx4 v[0:1], off
	v_lshl_add_u64 v[0:1], s[20:21], 0, v[134:135]
	s_add_i32 m0, s27, 0x1e000
	v_bfe_u32 v2, v8, 4, 2
	global_load_lds_dwordx4 v[0:1], off
	s_waitcnt vmcnt(8)
	s_barrier
	v_and_b32_e32 v0, 15, v8
	v_lshlrev_b32_e32 v1, 4, v2
	v_lshl_or_b32 v150, s18, 6, v0
	v_lshl_or_b32 v0, v0, 6, v1
	v_lshlrev_b32_e32 v1, 2, v8
	v_and_b32_e32 v1, 32, v1
	v_bitop3_b32 v3, v0, s19, v1 bitop3:0xde
	v_bitop3_b32 v151, v0, s23, v1 bitop3:0xde
	v_lshlrev_b32_e32 v0, 5, v2
	v_mov_b32_e32 v1, v131
	v_lshl_add_u64 v[0:1], s[8:9], 0, v[0:1]
	s_mov_b64 s[8:9], 0x200000
	v_lshl_add_u64 v[136:137], v[0:1], 0, s[8:9]
	v_lshlrev_b32_e32 v0, 15, v12
	v_and_b32_e32 v0, 0xffff0000, v0
	v_lshl_add_u32 v0, v13, 12, v0
	v_and_b32_e32 v1, 1, v12
	v_lshl_or_b32 v0, v1, 6, v0
	v_lshl_add_u32 v138, v14, 1, v0
	v_lshlrev_b32_e32 v0, 15, v9
	v_and_b32_e32 v0, 0xffff0000, v0
	s_waitcnt vmcnt(6)
	s_cmpk_lt_u32 s17, 0x100
	v_lshl_add_u32 v0, v10, 12, v0
	v_and_b32_e32 v1, 1, v9
	s_sext_i32_i8 s58, s16
	s_cselect_b64 s[16:17], -1, 0
	v_lshl_or_b32 v0, v1, 6, v0
	s_add_i32 s55, 0, 0x10000
	s_add_i32 s56, 0, 0x14000
	v_lshl_or_b32 v152, v2, 3, s22
	v_mov_b32_e32 v139, v131
	v_lshl_add_u32 v140, v11, 1, v0
	v_mov_b32_e32 v141, v131
	v_mov_b64_e32 v[142:143], 0x100
	v_mov_b64_e32 v[144:145], 0xff
	v_add_u32_e32 v153, s55, v151
	v_add_u32_e32 v154, s56, v151
	v_add_u32_e32 v155, 0, v3
	v_mbcnt_hi_u32_b32 v156, -1, v254
	v_mov_b32_e32 v157, 0x358637bd
	s_mov_b32 s57, 0x800000
	s_barrier
	s_branch .LBB0_724

.LBB0_942:
	s_add_u32 s16, s10, 0xf800000
	s_addc_u32 s17, s11, 0
	s_add_u32 s18, s10, 0xd800000
	s_mov_b64 s[20:21], 0x80
	s_addc_u32 s19, s11, 0
	s_and_b32 s61, s7, 3
	s_add_i32 m0, s59, 0x18000
	v_lshl_add_u64 v[6:7], v[6:7], 0, s[20:21]
	s_lshl_b32 s7, s8, 13
	s_lshl_b32 s9, s61, 12
	global_load_lds_dwordx4 v[6:7], off
	v_lshl_add_u64 v[4:5], v[4:5], 0, s[20:21]
	s_add_i32 m0, s59, 0x1a000
	s_add_i32 s62, s59, 0x8000
	s_add_i32 s63, s59, 0xa000
	global_load_lds_dwordx4 v[4:5], off
	v_lshl_add_u64 v[0:1], v[0:1], 0, s[20:21]
	s_mov_b32 m0, s62
	s_add_u32 s22, s52, 0x80080
	global_load_lds_dwordx4 v[0:1], off
	v_lshl_add_u64 v[0:1], v[2:3], 0, s[20:21]
	s_mov_b32 m0, s63
	s_addc_u32 s23, s53, 0
	global_load_lds_dwordx4 v[0:1], off
	s_add_i32 m0, s59, 0x1c000
	v_lshl_add_u64 v[0:1], s[22:23], 0, v[130:131]
	global_load_lds_dwordx4 v[0:1], off
	v_lshl_add_u64 v[0:1], s[22:23], 0, v[134:135]
	s_add_i32 m0, s59, 0x1e000
	s_nop 0
	global_load_lds_dwordx4 v[0:1], off
	s_waitcnt vmcnt(8)
	s_barrier
	s_cmpk_lt_u32 s6, 0x100
	v_bfe_u32 v1, v8, 4, 2
	v_and_b32_e32 v0, 15, v8
	v_lshlrev_b32_e32 v3, 4, v1
	v_lshl_or_b32 v148, s8, 6, v0
	v_lshl_or_b32 v0, v0, 6, v3
	v_lshlrev_b32_e32 v3, 2, v8
	v_and_b32_e32 v3, 32, v3
	v_bitop3_b32 v4, v0, s7, v3 bitop3:0xde
	v_bitop3_b32 v149, v0, s9, v3 bitop3:0xde
	v_lshlrev_b32_e32 v0, 15, v12
	v_and_b32_e32 v0, 0xffff0000, v0
	v_lshlrev_b32_e32 v2, 3, v1
	v_cmp_eq_u32_e64 s[6:7], 0, v1
	v_lshl_add_u32 v0, v13, 12, v0
	v_and_b32_e32 v1, 1, v12
	v_lshl_or_b32 v0, v1, 6, v0
	v_lshl_add_u32 v136, v14, 1, v0
	v_lshlrev_b32_e32 v0, 15, v9
	v_and_b32_e32 v0, 0xffff0000, v0
	s_waitcnt vmcnt(6)
	v_lshl_add_u32 v0, v10, 12, v0
	v_and_b32_e32 v1, 1, v9
	s_cselect_b64 s[22:23], -1, 0
	v_lshl_or_b32 v0, v1, 6, v0
	s_add_i32 s64, 0, 0x10000
	s_add_i32 s65, 0, 0x14000
	v_lshl_or_b32 v150, s61, 5, v2
	v_mov_b32_e32 v137, v131
	v_lshl_add_u32 v138, v11, 1, v0
	v_mov_b32_e32 v139, v131
	v_mov_b64_e32 v[140:141], 0x200
	v_mov_b64_e32 v[142:143], 0x1ff
	v_add_u32_e32 v151, s64, v149
	v_add_u32_e32 v152, s65, v149
	v_add_u32_e32 v153, 0, v4
	v_mbcnt_hi_u32_b32 v154, -1, v254
	s_mov_b32 s66, 0
	s_barrier
	s_branch .LBB0_945

.LBB0_1034:
	v_bfe_u32 v17, v12, 4, 2
	s_sext_i32_i16 s72, s12
	s_add_u32 s12, s6, 0x11800000
	v_and_b32_e32 v16, 15, v12
	v_lshlrev_b32_e32 v18, 4, v17
	v_lshlrev_b32_e32 v12, 2, v12
	s_addc_u32 s13, s7, 0
	v_lshl_or_b32 v219, s14, 6, v16
	v_lshl_or_b32 v16, v16, 6, v18
	s_lshl_b32 s14, s14, 13
	v_and_b32_e32 v12, 32, v12
	v_bitop3_b32 v18, v16, s14, v12 bitop3:0xde
	s_lshl_b32 s14, s18, 5
	s_and_b32 s20, s14, 0x60
	s_lshl_b32 s14, s20, 7
	v_bitop3_b32 v220, v16, s14, v12 bitop3:0xde
	s_mov_b64 s[14:15], 0x80
	s_add_i32 m0, s35, 0x18000
	v_lshl_add_u64 v[8:9], v[8:9], 0, s[14:15]
	global_load_lds_dwordx4 v[8:9], off
	v_lshl_add_u64 v[6:7], v[6:7], 0, s[14:15]
	s_add_i32 m0, s35, 0x1a000
	s_add_i32 s61, s35, 0x8000
	s_add_i32 s62, s35, 0xa000
	global_load_lds_dwordx4 v[6:7], off
	v_lshl_add_u64 v[2:3], v[2:3], 0, s[14:15]
	s_mov_b32 m0, s61
	s_add_u32 s18, s8, 0x80080
	global_load_lds_dwordx4 v[2:3], off
	v_lshl_add_u64 v[2:3], v[4:5], 0, s[14:15]
	s_mov_b32 m0, s62
	s_addc_u32 s19, s9, 0
	global_load_lds_dwordx4 v[2:3], off
	s_add_i32 m0, s35, 0x1c000
	v_lshl_add_u64 v[2:3], s[18:19], 0, v[198:199]
	global_load_lds_dwordx4 v[2:3], off
	v_lshl_add_u64 v[2:3], s[18:19], 0, v[202:203]
	s_add_i32 m0, s35, 0x1e000
	s_nop 0
	global_load_lds_dwordx4 v[2:3], off
	s_waitcnt vmcnt(8)
	s_barrier
	s_cmpk_lt_u32 s16, 0x100
	s_mul_i32 s18, s77, s73
	s_mul_hi_u32 s19, s77, s42
	s_cselect_b64 s[16:17], -1, 0
	s_add_i32 s18, s19, s18
	v_readlane_b32 s19, v255, 10
	s_mul_i32 s22, s77, s42
	s_add_u32 s22, s22, s19
	v_readlane_b32 s19, v255, 11
	s_addc_u32 s23, s18, s19
	s_cmpk_lt_i32 s22, 0x580
	s_cselect_b64 s[18:19], -1, 0
	s_ashr_i32 s24, s22, 31
	s_lshr_b32 s24, s24, 29
	s_add_i32 s24, s22, s24
	s_ashr_i32 s25, s24, 3
	s_and_b32 s24, s24, -8
	s_sub_i32 s24, s22, s24
	s_cmp_lt_i32 s24, 0
	s_cselect_b32 s26, s57, 0xb0
	s_mul_i32 s24, s26, s24
	s_add_i32 s24, s24, s25
	s_mul_hi_i32 s25, s24, 0x2e8ba2e9
	s_lshr_b32 s26, s25, 31
	s_ashr_i32 s25, s25, 6
	s_add_i32 s25, s25, s26
	s_lshl_b32 s26, s25, 3
	s_sub_i32 s27, 32, s26
	s_min_i32 s27, s27, 8
	s_abs_i32 s30, s27
	v_cvt_f32_u32_e32 v4, s30
	v_lshlrev_b32_e32 v2, 6, v17
	v_mov_b32_e32 v3, v0
	s_mulk_i32 s25, 0x160
	v_rcp_iflag_f32_e32 v4, v4
	v_lshl_add_u64 v[204:205], s[6:7], 0, v[2:3]
	s_sub_i32 s6, s24, s25
	s_sub_i32 s24, 0, s30
	v_mul_f32_e32 v4, 0x4f7ffffe, v4
	v_cvt_u32_f32_e32 v4, v4
	v_lshl_or_b32 v221, v17, 3, s20
	s_abs_i32 s20, s6
	s_xor_b32 s7, s6, s27
	v_readfirstlane_b32 s25, v4
	s_mul_i32 s24, s24, s25
	s_mul_hi_u32 s24, s25, s24
	s_add_i32 s25, s25, s24
	s_mul_hi_u32 s24, s20, s25
	s_mul_i32 s25, s24, s30
	s_sub_i32 s20, s20, s25
	s_ashr_i32 s7, s7, 31
	s_add_i32 s25, s24, 1
	s_sub_i32 s31, s20, s30
	s_cmp_ge_u32 s20, s30
	s_cselect_b32 s24, s25, s24
	v_lshlrev_b32_e32 v4, 15, v13
	s_cselect_b32 s20, s31, s20
	s_add_i32 s25, s24, 1
	v_and_b32_e32 v4, 0xffff0000, v4
	s_cmp_ge_u32 s20, s30
	v_lshl_add_u32 v4, v14, 12, v4
	v_and_b32_e32 v5, 1, v13
	s_cselect_b32 s20, s25, s24
	v_lshl_or_b32 v4, v5, 6, v4
	s_xor_b32 s20, s20, s7
	v_lshl_add_u32 v206, v15, 1, v4
	v_lshlrev_b32_e32 v4, 15, v1
	s_sub_i32 s63, s20, s7
	v_and_b32_e32 v4, 0xffff0000, v4
	s_waitcnt vmcnt(6)
	s_mul_i32 s7, s63, s27
	v_lshl_add_u32 v4, v10, 12, v4
	v_and_b32_e32 v1, 1, v1
	v_mov_b64_e32 v[2:3], 0x580
	s_sub_i32 s64, s6, s7
	v_lshl_or_b32 v1, v1, 6, v4
	s_add_i32 s65, 0, 0x10000
	s_add_i32 s66, 0, 0x14000
	s_add_i32 s64, s64, s26
	v_mov_b32_e32 v207, v0
	v_lshl_add_u32 v208, v11, 1, v1
	v_mov_b32_e32 v209, v0
	v_cmp_lt_i64_e64 s[6:7], s[22:23], v[2:3]
	v_add_u32_e32 v222, s65, v220
	v_add_u32_e32 v223, s66, v220
	v_add_u32_e32 v224, 0, v18
	v_mbcnt_hi_u32_b32 v225, -1, v254
	v_mov_b32_e32 v226, 0x358637bd
	s_mov_b32 s67, 0x800000
	s_movk_i32 s68, 0x2c00
	v_mov_b64_e32 v[210:211], 0x57f
	s_barrier
	s_branch .LBB0_1037

.LBB0_1123:
	s_add_u32 s16, s6, 0xf800000
	s_addc_u32 s17, s7, 0
	s_add_u32 s18, s6, 0xd800000
	s_addc_u32 s19, s7, 0
	s_add_u32 s20, s6, 0x200000
	s_mov_b64 s[22:23], 0x80
	s_addc_u32 s21, s7, 0
	s_and_b32 s57, s9, 3
	s_add_i32 m0, s53, 0x18000
	v_lshl_add_u64 v[6:7], v[6:7], 0, s[22:23]
	s_lshl_b32 s9, s11, 13
	s_lshl_b32 s24, s57, 12
	global_load_lds_dwordx4 v[6:7], off
	v_lshl_add_u64 v[2:3], v[2:3], 0, s[22:23]
	s_add_i32 m0, s53, 0x1a000
	s_add_i32 s58, s53, 0x8000
	s_add_i32 s59, s53, 0xa000
	global_load_lds_dwordx4 v[2:3], off
	v_lshl_add_u64 v[0:1], v[0:1], 0, s[22:23]
	s_mov_b32 m0, s58
	s_add_u32 s6, s34, 0x160080
	global_load_lds_dwordx4 v[0:1], off
	v_lshl_add_u64 v[0:1], v[4:5], 0, s[22:23]
	s_mov_b32 m0, s59
	s_addc_u32 s7, s35, 0
	global_load_lds_dwordx4 v[0:1], off
	s_add_i32 m0, s53, 0x1c000
	v_lshl_add_u64 v[0:1], s[6:7], 0, v[130:131]
	global_load_lds_dwordx4 v[0:1], off
	v_lshl_add_u64 v[0:1], s[6:7], 0, v[134:135]
	s_add_i32 m0, s53, 0x1e000
	s_nop 0
	global_load_lds_dwordx4 v[0:1], off
	s_waitcnt vmcnt(8)
	s_barrier
	s_cmpk_lt_u32 s10, 0x100
	v_bfe_u32 v0, v8, 4, 2
	v_and_b32_e32 v1, 15, v8
	v_lshlrev_b32_e32 v3, 4, v0
	v_lshl_or_b32 v148, s11, 6, v1
	v_lshl_or_b32 v1, v1, 6, v3
	v_lshlrev_b32_e32 v3, 2, v8
	v_and_b32_e32 v3, 32, v3
	v_lshlrev_b32_e32 v2, 3, v0
	v_bitop3_b32 v4, v1, s9, v3 bitop3:0xde
	v_bitop3_b32 v149, v1, s24, v3 bitop3:0xde
	v_cmp_eq_u32_e64 s[6:7], 0, v0
	v_lshrrev_b32_e32 v1, 1, v13
	v_mul_lo_u32 v0, v14, s8
	v_mad_u64_u32 v[0:1], s[10:11], v1, s26, v[0:1]
	v_or_b32_e32 v0, v0, v15
	s_mov_b64 s[36:37], 0x160080
	v_add_lshl_u32 v0, v0, v16, 1
	v_mov_b32_e32 v1, v131
	v_lshl_add_u64 v[136:137], v[0:1], 0, s[36:37]
	v_lshrrev_b32_e32 v1, 1, v9
	v_mul_lo_u32 v0, v10, s8
	v_mad_u64_u32 v[0:1], s[8:9], v1, s26, v[0:1]
	s_waitcnt vmcnt(6)
	v_or_b32_e32 v0, v0, v11
	s_cselect_b64 s[24:25], -1, 0
	v_add_lshl_u32 v0, v0, v12, 1
	v_mov_b32_e32 v1, v131
	s_add_i32 s60, 0, 0x10000
	s_add_i32 s61, 0, 0x14000
	v_lshl_or_b32 v150, s57, 5, v2
	v_lshl_add_u64 v[138:139], v[0:1], 0, s[36:37]
	v_mov_b64_e32 v[140:141], 0x100
	v_mov_b64_e32 v[142:143], 0xff
	v_add_u32_e32 v151, s60, v149
	v_add_u32_e32 v152, s61, v149
	v_add_u32_e32 v153, 0, v4
	v_mbcnt_hi_u32_b32 v154, -1, v254
	s_mov_b32 s62, 0
	s_barrier
	s_branch .LBB0_1126

.LBB0_1219:
	v_bfe_u32 v148, v9, 4, 2
	v_and_b32_e32 v149, 15, v9
	v_lshlrev_b32_e32 v15, 4, v148
	v_lshlrev_b32_e32 v9, 2, v9
	s_mov_b64 s[18:19], 0x80
	s_and_b32 s44, s5, 3
	v_lshl_or_b32 v15, v149, 6, v15
	s_lshl_b32 s0, s20, 13
	v_and_b32_e32 v9, 32, v9
	s_add_i32 m0, s48, 0x18000
	v_lshl_add_u64 v[6:7], v[6:7], 0, s[18:19]
	s_lshl_b32 s52, s20, 6
	v_bitop3_b32 v16, v15, s0, v9 bitop3:0xde
	s_lshl_b32 s0, s44, 12
	global_load_lds_dwordx4 v[6:7], off
	v_lshl_add_u64 v[4:5], v[4:5], 0, s[18:19]
	s_add_i32 m0, s48, 0x1a000
	s_add_i32 s54, s48, 0x8000
	s_add_i32 s55, s48, 0xa000
	s_sext_i32_i8 s15, s4
	global_load_lds_dwordx4 v[4:5], off
	v_lshl_add_u64 v[2:3], v[2:3], 0, s[18:19]
	s_mov_b32 m0, s54
	s_add_u32 s4, s30, 0x80080
	global_load_lds_dwordx4 v[2:3], off
	v_lshl_add_u64 v[0:1], v[0:1], 0, s[18:19]
	s_mov_b32 m0, s55
	s_addc_u32 s5, s31, 0
	global_load_lds_dwordx4 v[0:1], off
	s_add_i32 m0, s48, 0x1c000
	v_lshl_add_u64 v[0:1], s[4:5], 0, v[130:131]
	global_load_lds_dwordx4 v[0:1], off
	v_lshl_add_u64 v[0:1], s[4:5], 0, v[134:135]
	s_add_i32 m0, s48, 0x1e000
	v_bitop3_b32 v150, v15, s0, v9 bitop3:0xde
	global_load_lds_dwordx4 v[0:1], off
	s_waitcnt vmcnt(8)
	s_barrier
	v_lshlrev_b32_e32 v0, 15, v12
	v_and_b32_e32 v0, 0xffff0000, v0
	v_lshl_add_u32 v0, v13, 12, v0
	v_and_b32_e32 v1, 1, v12
	v_lshl_or_b32 v0, v1, 6, v0
	s_mov_b64 s[0:1], 0x80080
	v_lshl_add_u32 v0, v14, 1, v0
	v_mov_b32_e32 v1, v131
	v_lshl_add_u64 v[136:137], v[0:1], 0, s[0:1]
	v_lshlrev_b32_e32 v0, 15, v8
	v_and_b32_e32 v0, 0xffff0000, v0
	v_lshl_add_u32 v0, v10, 12, v0
	v_and_b32_e32 v1, 1, v8
	s_waitcnt vmcnt(6)
	v_lshl_or_b32 v0, v1, 6, v0
	v_lshl_add_u32 v0, v11, 1, v0
	v_mov_b32_e32 v1, v131
	v_lshl_add_u64 v[138:139], v[0:1], 0, s[0:1]
	v_mov_b64_e32 v[140:141], 0x100
	v_mov_b64_e32 v[142:143], 0xff
	s_add_i32 s56, 0, 0x10000
	s_add_i32 s57, 0, 0x14000
	v_add_u32_e32 v151, 0, v16
	v_mov_b32_e32 v0, v131
	v_mov_b32_e32 v2, v131
	v_mov_b32_e32 v3, v131
	v_mov_b32_e32 v4, v131
	v_mov_b32_e32 v5, v131
	v_mov_b32_e32 v6, v131
	v_mov_b32_e32 v7, v131
	v_mov_b32_e32 v16, v131
	v_mov_b32_e32 v17, v131
	v_mov_b32_e32 v18, v131
	v_mov_b32_e32 v19, v131
	v_mov_b32_e32 v20, v131
	v_mov_b32_e32 v21, v131
	v_mov_b32_e32 v22, v131
	v_mov_b32_e32 v23, v131
	v_mov_b32_e32 v32, v131
	v_mov_b32_e32 v33, v131
	v_mov_b32_e32 v34, v131
	v_mov_b32_e32 v35, v131
	v_mov_b32_e32 v36, v131
	v_mov_b32_e32 v37, v131
	v_mov_b32_e32 v38, v131
	v_mov_b32_e32 v39, v131
	v_mov_b32_e32 v48, v131
	v_mov_b32_e32 v49, v131
	v_mov_b32_e32 v50, v131
	v_mov_b32_e32 v51, v131
	v_mov_b32_e32 v52, v131
	v_mov_b32_e32 v53, v131
	v_mov_b32_e32 v54, v131
	v_mov_b32_e32 v55, v131
	v_mov_b32_e32 v8, v131
	v_mov_b32_e32 v9, v131
	v_mov_b32_e32 v10, v131
	v_mov_b32_e32 v11, v131
	v_mov_b32_e32 v12, v131
	v_mov_b32_e32 v13, v131
	v_mov_b32_e32 v14, v131
	v_mov_b32_e32 v15, v131
	v_mov_b32_e32 v24, v131
	v_mov_b32_e32 v25, v131
	v_mov_b32_e32 v26, v131
	v_mov_b32_e32 v27, v131
	v_mov_b32_e32 v28, v131
	v_mov_b32_e32 v29, v131
	v_mov_b32_e32 v30, v131
	v_mov_b32_e32 v31, v131
	v_mov_b32_e32 v40, v131
	v_mov_b32_e32 v41, v131
	v_mov_b32_e32 v42, v131
	v_mov_b32_e32 v43, v131
	v_mov_b32_e32 v44, v131
	v_mov_b32_e32 v45, v131
	v_mov_b32_e32 v46, v131
	v_mov_b32_e32 v47, v131
	s_waitcnt vmcnt(0)
	v_mov_b32_e32 v56, v131
	v_mov_b32_e32 v57, v131
	v_mov_b32_e32 v58, v131
	v_mov_b32_e32 v59, v131
	v_mov_b32_e32 v60, v131
	v_mov_b32_e32 v61, v131
	v_mov_b32_e32 v62, v131
	v_mov_b32_e32 v63, v131
	v_mov_b32_e32 v64, v131
	v_mov_b32_e32 v65, v131
	v_mov_b32_e32 v66, v131
	v_mov_b32_e32 v67, v131
	v_mov_b32_e32 v68, v131
	v_mov_b32_e32 v69, v131
	v_mov_b32_e32 v70, v131
	v_mov_b32_e32 v71, v131
	v_mov_b32_e32 v80, v131
	v_mov_b32_e32 v81, v131
	v_mov_b32_e32 v82, v131
	v_mov_b32_e32 v83, v131
	v_mov_b32_e32 v84, v131
	v_mov_b32_e32 v85, v131
	v_mov_b32_e32 v86, v131
	v_mov_b32_e32 v87, v131
	v_mov_b32_e32 v96, v131
	v_mov_b32_e32 v97, v131
	v_mov_b32_e32 v98, v131
	v_mov_b32_e32 v99, v131
	v_mov_b32_e32 v100, v131
	v_mov_b32_e32 v101, v131
	v_mov_b32_e32 v102, v131
	v_mov_b32_e32 v103, v131
	v_mov_b32_e32 v112, v131
	v_mov_b32_e32 v113, v131
	v_mov_b32_e32 v114, v131
	v_mov_b32_e32 v115, v131
	v_mov_b32_e32 v116, v131
	v_mov_b32_e32 v117, v131
	v_mov_b32_e32 v118, v131
	v_mov_b32_e32 v119, v131
	v_mov_b32_e32 v72, v131
	v_mov_b32_e32 v73, v131
	v_mov_b32_e32 v74, v131
	v_mov_b32_e32 v75, v131
	v_mov_b32_e32 v76, v131
	v_mov_b32_e32 v77, v131
	v_mov_b32_e32 v78, v131
	v_mov_b32_e32 v79, v131
	v_mov_b32_e32 v88, v131
	v_mov_b32_e32 v89, v131
	v_mov_b32_e32 v90, v131
	v_mov_b32_e32 v91, v131
	v_mov_b32_e32 v92, v131
	v_mov_b32_e32 v93, v131
	v_mov_b32_e32 v94, v131
	v_mov_b32_e32 v95, v131
	v_mov_b32_e32 v104, v131
	v_mov_b32_e32 v105, v131
	v_mov_b32_e32 v106, v131
	v_mov_b32_e32 v107, v131
	v_mov_b32_e32 v108, v131
	v_mov_b32_e32 v109, v131
	v_mov_b32_e32 v110, v131
	v_mov_b32_e32 v111, v131
	v_mov_b32_e32 v120, v131
	v_mov_b32_e32 v121, v131
	v_mov_b32_e32 v122, v131
	v_mov_b32_e32 v123, v131
	v_mov_b32_e32 v124, v131
	v_mov_b32_e32 v125, v131
	v_mov_b32_e32 v126, v131
	v_mov_b32_e32 v127, v131
	s_barrier
